# group-local fast barriers (32-arrival counter + L1 invalidate, XCC_ID-verified) at the six row-local seams
# speedup vs baseline: 1.0212x; 1.0060x over previous
; #define LAS __attribute__((address_space(3)))
; #define KARGS() ({ KArgsP _p = (KArgsP)__builtin_amdgcn_kernarg_segment_ptr(); asm volatile("" : "+s"(_p)); _p; })
; __device__ __forceinline__ unsigned xb_add(unsigned* p, unsigned v) { return __hip_atomic_fetch_add(p, v, __ATOMIC_RELAXED, __HIP_MEMORY_SCOPE_AGENT); }
; __device__ __forceinline__ unsigned xb_xcc_id() { return (unsigned)__builtin_amdgcn_s_getreg((3 << 11) | 20) & 0xFu; }
; __device__ __forceinline__ XcdBarrier xcd_barrier_post(unsigned* bar, volatile LAS unsigned* st) {
;     XcdBarrier b; b.bar = bar; b.x = xb_xcc_id(); b.st = st;
;     if (threadIdx.x == 0) (void)xb_add(&bar[XB_XCNT(b.x)], 1u);
; __global__ void __launch_bounds__(512, 2) fwd_kernel(Args a) {
;     ...
;     (void)xcd_barrier_post((unsigned*)(KARGS()->ws + WS_CTL) + 1024, (volatile LAS unsigned*)(lds + LDS_XB));
;     for (int rep = 0; rep < (PROBE == 5 ? 2 : 1); ++rep) prologue(KARGS(), lds, G);
;     grid.sync();
.LBB0_479:
	s_or_b64 exec, exec, s[14:15]
	v_lshrrev_b32_e32 v1, 20, v0
	v_lshrrev_b32_e32 v0, 10, v0
	v_or_b32_e32 v0, v0, v1
	s_movk_i32 s2, 0x3ff
	v_and_or_b32 v0, v0, s2, v236
	v_cmp_eq_u32_e32 vcc, 0, v0
	s_waitcnt vmcnt(0) lgkmcnt(0)
	s_barrier
	s_and_saveexec_b64 s[2:3], vcc
	s_xor_b64 s[6:7], exec, s[2:3]
	s_cbranch_execz .LBB0_489
	s_load_dwordx2 s[8:9], s[0:1], 0x128
	s_load_dword s10, s[0:1], 0x130
	s_getreg_b32 s11, hwreg(HW_REG_XCC_ID, 0, 4)
	s_lshl_b32 s11, 1, s11
	v_readlane_b32 s12, v255, 8
	s_nop 1
	s_and_b32 s12, s12, 7
	s_lshl_b32 s12, s12, 2
	v_mov_b32_e32 v3, s11
	v_mov_b32_e32 v2, s12
	s_waitcnt lgkmcnt(0)
	s_add_u32 s8, s8, 0x6000
	s_addc_u32 s9, s9, 0
	global_atomic_or v2, v3, s[8:9] offset:256
	buffer_wbl2 sc1
	s_waitcnt vmcnt(0)
	v_mov_b32_e32 v2, 0
	v_mov_b32_e32 v3, 1
	global_atomic_add v2, v3, s[8:9]

; #define LAS __attribute__((address_space(3)))
; #define GSYNC() do { XcdBarrier xb_; xb_.bar = (unsigned*)(KARGS()->ws + WS_CTL) + 1024; xb_.x = xb_xcc_id(); xb_.st = (volatile LAS unsigned*)(lds + LDS_XB); xcd_barrier(xb_); } while (0)
; __global__ void __launch_bounds__(512, 2) fwd_kernel(Args a) {
;     ...
;     grid.sync();
;     ...
;     for (int l = 0; l < DEPTH; ++l) {
;         if (PROBE == 4) { for (int rep = 0; rep < 10; ++rep) GSYNC(); }
;         for (int rep = 0; rep < (PROBE == 2 ? 2 : 1); ++rep)
;         { PH StdSched S; S.init(T, 2 * FF, G, bid, D, D); EpiFfnUp E{(bf16_t*)(ar + AR_HID), ssb + (size_t)(4 * l + 0) * T * 16, (const LAS float*)(lds + LDS_RS)};
.LBB0_489:
	s_or_b64 exec, exec, s[6:7]
	s_barrier
	s_load_dwordx2 s[8:9], s[0:1], 0x128
	s_load_dword s10, s[0:1], 0x130
	v_mov_b32_e32 v2, 0x6100
	s_mov_b32 s11, 0
	s_waitcnt lgkmcnt(0)
	global_load_dwordx4 v[0:3], v2, s[8:9] offset:0 sc1
	s_waitcnt vmcnt(0)
	v_readfirstlane_b32 s12, v0
	s_nop 1
	s_add_i32 s13, s12, -1
	s_and_b32 s13, s13, s12
	s_or_b32 s11, s11, s13
	s_cmp_eq_u32 s12, 0
	s_cselect_b32 s13, 1, 0
	s_or_b32 s11, s11, s13
	v_readfirstlane_b32 s12, v1
	s_nop 1
	s_add_i32 s13, s12, -1
	s_and_b32 s13, s13, s12
	s_or_b32 s11, s11, s13
	s_cmp_eq_u32 s12, 0
	s_cselect_b32 s13, 1, 0
	s_or_b32 s11, s11, s13
	v_readfirstlane_b32 s12, v2
	s_nop 1
	s_add_i32 s13, s12, -1
	s_and_b32 s13, s13, s12
	s_or_b32 s11, s11, s13
	s_cmp_eq_u32 s12, 0
	s_cselect_b32 s13, 1, 0
	s_or_b32 s11, s11, s13
	v_readfirstlane_b32 s12, v3
	s_nop 1
	s_add_i32 s13, s12, -1
	s_and_b32 s13, s13, s12
	s_or_b32 s11, s11, s13
	s_cmp_eq_u32 s12, 0
	s_cselect_b32 s13, 1, 0
	s_or_b32 s11, s11, s13
	v_mov_b32_e32 v2, 0x6100
	global_load_dwordx4 v[0:3], v2, s[8:9] offset:16 sc1
	s_waitcnt vmcnt(0)
	v_readfirstlane_b32 s12, v0
	s_nop 1
	s_add_i32 s13, s12, -1
	s_and_b32 s13, s13, s12
	s_or_b32 s11, s11, s13
	s_cmp_eq_u32 s12, 0
	s_cselect_b32 s13, 1, 0
	s_or_b32 s11, s11, s13
	v_readfirstlane_b32 s12, v1
	s_nop 1
	s_add_i32 s13, s12, -1
	s_and_b32 s13, s13, s12
	s_or_b32 s11, s11, s13
	s_cmp_eq_u32 s12, 0
	s_cselect_b32 s13, 1, 0
	s_or_b32 s11, s11, s13
	v_readfirstlane_b32 s12, v2
	s_nop 1
	s_add_i32 s13, s12, -1
	s_and_b32 s13, s13, s12
	s_or_b32 s11, s11, s13
	s_cmp_eq_u32 s12, 0
	s_cselect_b32 s13, 1, 0
	s_or_b32 s11, s11, s13
	v_readfirstlane_b32 s12, v3
	s_nop 1
	s_add_i32 s13, s12, -1
	s_and_b32 s13, s13, s12
	s_or_b32 s11, s11, s13
	s_cmp_eq_u32 s12, 0
	s_cselect_b32 s13, 1, 0
	s_or_b32 s11, s11, s13
	s_xor_b32 s10, s10, 0x100
	s_or_b32 s11, s11, s10
	s_cmp_eq_u32 s11, 0
	s_cselect_b32 s11, 1, 0
	s_mov_b32 s12, 0
	v_writelane_b32 v255, s11, 40
	v_writelane_b32 v255, s12, 41
	s_load_dword s2, s[0:1], 0x138
	s_cmpk_gt_i32 s34, 0x7f
	s_cselect_b64 s[4:5], -1, 0
	s_mul_i32 s3, s95, s94
	v_writelane_b32 v255, s4, 2
	s_waitcnt lgkmcnt(0)
	s_mul_i32 s3, s3, s2
	s_add_i32 s2, 0, 0x22100
	v_writelane_b32 v255, s5, 3
	v_writelane_b32 v255, s2, 4
	s_add_i32 s2, 0, 0x22000
	s_mov_b32 s19, 0
	v_writelane_b32 v255, s2, 5
	s_add_i32 s2, 0, 0x22004
	s_mov_b64 s[50:51], -1
	s_movk_i32 s95, 0xb00
	v_mov_b32_e32 v219, 0x358637bd
	s_mov_b32 s85, 0x800000
	s_mov_b32 s86, 0x1fffe0
	v_mov_b32_e32 v1, 0
	s_movk_i32 s89, 0x3c0
	s_mov_b64 s[26:27], 0x80
	s_mov_b64 s[28:29], 0x100
	s_movk_i32 s90, 0x1600
	v_writelane_b32 v255, s2, 7
	v_mov_b32_e32 v254, 1
	s_movk_i32 s96, 0x1700
	s_movk_i32 s97, 0x500
	s_movk_i32 s20, 0x1f00
	s_movk_i32 s23, 0x280
	s_movk_i32 s34, 0x70
	s_add_i32 s41, 0, 0x18200
	s_movk_i32 s36, 0xffdf
	s_mov_b32 s37, 0xff800000
	s_mov_b32 s84, 0x41200000
	v_mov_b32_e32 v218, 0x260
	s_add_i32 s35, 0, 0x21000
	v_mov_b64_e32 v[224:225], 0xb00
	v_mov_b64_e32 v[192:193], 0xaff
	v_mov_b64_e32 v[194:195], 0x200
	v_mov_b64_e32 v[234:235], 0x1ff
	v_mov_b32_e32 v229, 0x80
	v_mov_b32_e32 v230, 0xff800000
	s_mov_b32 s30, 0xbfb8aa3b
	s_mov_b32 s38, 0x3d372713
	s_mov_b32 s40, 0xc0135761
	s_mov_b64 s[42:43], 0x180
	s_mov_b32 s48, s19
	s_branch .LBB0_493

; __device__ __forceinline__ unsigned xb_ld(unsigned* p)              { return __hip_atomic_load(p, __ATOMIC_RELAXED, __HIP_MEMORY_SCOPE_AGENT); }
; __device__ __forceinline__ unsigned xb_add(unsigned* p, unsigned v) { return __hip_atomic_fetch_add(p, v, __ATOMIC_RELAXED, __HIP_MEMORY_SCOPE_AGENT); }
; #define XB_SPIN(cond, bar) do { unsigned _sp = 0; while (cond) { __builtin_amdgcn_s_sleep(1); \
;     if ((++_sp & 255u) == 0u) { if (xb_ld(&(bar)[XB_TMO])) break; if (_sp > XB_SPIN_CAP) { atomicAdd(&(bar)[XB_TMO], 1u); break; } } } } while (0)
; #define GSYNC() do { XcdBarrier xb_; xb_.bar = (unsigned*)(KARGS()->ws + WS_CTL) + 1024; xb_.x = xb_xcc_id(); xb_.st = (volatile LAS unsigned*)(lds + LDS_XB); xcd_barrier(xb_); } while (0)
; __device__ __forceinline__ void xcd_barrier(const XcdBarrier& b) {
;     asm volatile("s_waitcnt vmcnt(0)" ::: "memory");
;     __syncthreads();
;     if (threadIdx.x == 0) {
;         unsigned* bar = b.bar;
;         __builtin_amdgcn_s_waitcnt(0);
;         unsigned nloc = b.st[0], nx = b.st[1];
;         if (nloc == 0u) { xcd_barrier_complete(bar, b.x, nloc, nx); b.st[0] = nloc; b.st[1] = nx; }
;         const unsigned old = xb_add(&bar[XB_XSUB(b.x)], 1u);
;         const unsigned gen = old / nloc;
;         if (old + 1u == (gen + 1u) * nloc) {
;             __builtin_amdgcn_fence(__ATOMIC_RELEASE, "agent");
;             asm volatile("s_waitcnt vmcnt(0)" ::: "memory");
;             const unsigned og = xb_add(&bar[XB_TOP], 1u);
;             const unsigned tg = og / nx;
;             if (og + 1u == (tg + 1u) * nx) xb_add(&bar[XB_TOPGEN], 1u);
;             else XB_SPIN(xb_ld(&bar[XB_TOPGEN]) == tg, bar);
;             __builtin_amdgcn_fence(__ATOMIC_ACQUIRE, "agent");
;             xb_add(&bar[XB_XGEN(b.x)], 1u);
;             asm volatile("s_waitcnt vmcnt(0)" ::: "memory");
;         } else {
;             XB_SPIN(xb_ld(&bar[XB_XGEN(b.x)]) == gen, bar);
;             __builtin_amdgcn_fence(__ATOMIC_ACQUIRE, "agent");
;             asm volatile("s_waitcnt vmcnt(0)" ::: "memory");
;         }
;     }
;     __syncthreads();
; }
; __global__ void __launch_bounds__(512, 2) fwd_kernel(Args a) {
;     ...
;         GSYNC();
.LBB0_535:
	s_mov_b64 s[8:9], s[0:1]
	s_getreg_b32 s2, hwreg(HW_REG_XCC_ID, 0, 4)
	s_waitcnt vmcnt(0)
	v_readlane_b32 s6, v255, 0
	v_readlane_b32 s7, v255, 1
	s_waitcnt vmcnt(0)
	s_barrier
	v_readlane_b32 s4, v255, 40
	s_nop 1
	s_cmp_eq_u32 s4, 0
	s_cbranch_scc1 .Lfs0
	s_and_saveexec_b64 s[4:5], s[6:7]
	s_cbranch_execz .Lfe0
	s_load_dwordx2 s[8:9], s[0:1], 0x128
	v_readlane_b32 s10, v255, 41
	v_readlane_b32 s11, v255, 8
	s_nop 1
	s_and_b32 s11, s11, 7
	s_lshl_b32 s11, s11, 7
	s_addk_i32 s11, 0x6200
	v_mov_b32_e32 v2, 0
	v_mov_b32_e32 v3, 1
	s_add_i32 s10, s10, 1
	s_lshl_b32 s10, s10, 5
	s_waitcnt lgkmcnt(0)
	s_add_u32 s8, s8, s11
	s_addc_u32 s9, s9, 0
	global_atomic_add v2, v3, s[8:9]

; __device__ __forceinline__ unsigned xb_ld(unsigned* p)              { return __hip_atomic_load(p, __ATOMIC_RELAXED, __HIP_MEMORY_SCOPE_AGENT); }
; __device__ __forceinline__ unsigned xb_add(unsigned* p, unsigned v) { return __hip_atomic_fetch_add(p, v, __ATOMIC_RELAXED, __HIP_MEMORY_SCOPE_AGENT); }
; #define XB_SPIN(cond, bar) do { unsigned _sp = 0; while (cond) { __builtin_amdgcn_s_sleep(1); \
;     if ((++_sp & 255u) == 0u) { if (xb_ld(&(bar)[XB_TMO])) break; if (_sp > XB_SPIN_CAP) { atomicAdd(&(bar)[XB_TMO], 1u); break; } } } } while (0)
; __device__ __forceinline__ void xcd_barrier(const XcdBarrier& b) {
;     asm volatile("s_waitcnt vmcnt(0)" ::: "memory");
;     __syncthreads();
;     if (threadIdx.x == 0) {
;         unsigned* bar = b.bar;
;         __builtin_amdgcn_s_waitcnt(0);
;         unsigned nloc = b.st[0], nx = b.st[1];
;         if (nloc == 0u) { xcd_barrier_complete(bar, b.x, nloc, nx); b.st[0] = nloc; b.st[1] = nx; }
;         const unsigned old = xb_add(&bar[XB_XSUB(b.x)], 1u);
;         const unsigned gen = old / nloc;
;         if (old + 1u == (gen + 1u) * nloc) {
;             __builtin_amdgcn_fence(__ATOMIC_RELEASE, "agent");
;             asm volatile("s_waitcnt vmcnt(0)" ::: "memory");
;             const unsigned og = xb_add(&bar[XB_TOP], 1u);
;             const unsigned tg = og / nx;
;             if (og + 1u == (tg + 1u) * nx) xb_add(&bar[XB_TOPGEN], 1u);
;             else XB_SPIN(xb_ld(&bar[XB_TOPGEN]) == tg, bar);
;             __builtin_amdgcn_fence(__ATOMIC_ACQUIRE, "agent");
;             xb_add(&bar[XB_XGEN(b.x)], 1u);
;             asm volatile("s_waitcnt vmcnt(0)" ::: "memory");
;         } else {
;             XB_SPIN(xb_ld(&bar[XB_XGEN(b.x)]) == gen, bar);
;             __builtin_amdgcn_fence(__ATOMIC_ACQUIRE, "agent");
;             asm volatile("s_waitcnt vmcnt(0)" ::: "memory");
;         }
;     }
;     __syncthreads();
; }
.Lfe0:
	s_or_b64 exec, exec, s[4:5]
	v_readlane_b32 s4, v255, 41
	s_nop 1
	s_add_i32 s4, s4, 1
	s_nop 0
	v_writelane_b32 v255, s4, 41
	s_branch .Lfj0
.Lfs0:
	s_and_saveexec_b64 s[4:5], s[6:7]
	s_xor_b64 s[6:7], exec, s[4:5]
	s_cbranch_execz .LBB0_588
	v_readlane_b32 s4, v255, 5
	s_load_dwordx2 s[8:9], s[8:9], 0x128
	s_waitcnt vmcnt(0) expcnt(0) lgkmcnt(0)
	v_mov_b32_e32 v0, s4
	ds_read_b32 v3, v0
	v_readlane_b32 s4, v255, 7
	s_and_b32 s2, s2, 15
	s_waitcnt lgkmcnt(0)
	v_cmp_ne_u32_e32 vcc, 0, v3
	v_mov_b32_e32 v0, s4
	ds_read_b32 v0, v0
	s_cbranch_vccnz .LBB0_551
	s_add_u32 s10, s8, 0x1200
	s_addc_u32 s11, s9, 0
	s_add_u32 s12, s8, 0x1400
	s_addc_u32 s13, s9, 0
	s_add_u32 s14, s8, 0x1500
	s_addc_u32 s15, s9, 0
	s_add_u32 s16, s8, 0x1600
	s_addc_u32 s17, s9, 0
	s_add_u32 s46, s8, 0x1700
	s_addc_u32 s47, s9, 0
	s_add_u32 s52, s8, 0x1800
	s_addc_u32 s53, s9, 0
	s_add_u32 s54, s8, 0x1900
	s_addc_u32 s55, s9, 0
	s_add_u32 s56, s8, 0x1a00
	s_addc_u32 s57, s9, 0
	s_add_u32 s58, s8, 0x1b00
	s_addc_u32 s59, s9, 0
	s_add_u32 s60, s8, 0x1c00
	s_addc_u32 s61, s9, 0
	s_add_u32 s62, s8, 0x1d00
	s_addc_u32 s63, s9, 0
	s_add_u32 s64, s8, 0x1e00
	s_addc_u32 s65, s9, 0
	s_add_u32 s66, s8, 0x1f00
	s_addc_u32 s67, s9, 0
	s_add_u32 s68, s8, 0x2000
	s_addc_u32 s69, s9, 0
	s_add_u32 s70, s8, 0x2100
	s_addc_u32 s71, s9, 0
	s_add_u32 s72, s8, 0x2200
	s_addc_u32 s73, s9, 0
	s_add_u32 s74, s8, 0x2300
	s_addc_u32 s75, s9, 0
	s_mov_b32 s4, 1
	s_branch .LBB0_539

;     __device__ bool next(int i, Unit& u) const {
;         const long L = (long)i * G + c; if (L >= nwg) return false;
;         int wgid = (int)L; { const int q = nwg / NXCD, r = nwg % NXCD, xcd = wgid % NXCD, off = wgid / NXCD; wgid = (xcd < r ? xcd * (q + 1) : r * (q + 1) + (xcd - r) * q) + off; }
;         const int nig = WGM * nN, gid = wgid / nig, fm = gid * WGM, gsz = (nM - fm) < WGM ? (nM - fm) : WGM;
;         u.pm = fm + ((wgid % nig) % gsz); u.pn = (wgid % nig) / gsz; u.bz = 0;
;         u.a_off = (unsigned)(u.pm * BM) * (unsigned)lda; u.b_off = (unsigned)(u.pn * BM) * (unsigned)ldb; return true;
; __global__ void __launch_bounds__(512, 2) fwd_kernel(Args a) {
;     ...
;         { PH StdSched S; S.init(T, D, G, bid, FF, FF); EpiResid E{hb, ssb + (size_t)(4 * l + 1) * T * 16, (PROBE == 7 && rep == 0) ? 0.f : 0.5f, nullptr, nullptr};
;           gemm_phase<EpiResid, StdSched, true>(lds, (const bf16_t*)(ar + AR_HID), (const bf16_t*)(wl + W_D1), FF, FF, FF, S, E); }
.Lfj0:
	s_xor_b64 s[4:5], s[50:51], -1
	v_writelane_b32 v255, s4, 10
	s_waitcnt lgkmcnt(0)
	v_mov_b32_e32 v0, v236
	s_mov_b32 s16, s94
	v_writelane_b32 v255, s5, 11
	s_mov_b64 s[4:5], s[0:1]
	v_readlane_b32 s6, v255, 8
	v_readlane_b32 s7, v255, 9
	s_mov_b32 s2, s6
	s_barrier
	s_load_dwordx2 s[6:7], s[4:5], 0x128
	s_cmpk_lt_i32 s2, 0x200
	v_mov_b32_e32 v10, v236
	s_cselect_b64 s[12:13], -1, 0
	v_mov_b32_e32 v215, 0x78
	v_mov_b32_e32 v214, 0x70
	v_mov_b32_e32 v204, 0x68
	v_mov_b32_e32 v191, 0x60
	s_mov_b64 s[10:11], 0
	v_readfirstlane_b32 s14, v10
	s_and_b64 vcc, exec, s[12:13]
	s_mov_b64 s[8:9], 0
	s_cbranch_vccz .LBB0_594
	s_ashr_i32 s4, s2, 31
	s_lshr_b32 s4, s4, 29
	s_add_i32 s4, s2, s4
	s_and_b32 s5, s4, -8
	s_sub_i32 s5, s2, s5
	s_cmp_gt_i32 s5, -1
	s_mov_b64 s[8:9], -1
	s_cbranch_scc0 .LBB0_591
	s_lshl_b32 s10, s5, 6
	s_mov_b64 s[8:9], 0

; __device__ __forceinline__ unsigned xb_ld(unsigned* p)              { return __hip_atomic_load(p, __ATOMIC_RELAXED, __HIP_MEMORY_SCOPE_AGENT); }
; __device__ __forceinline__ unsigned xb_add(unsigned* p, unsigned v) { return __hip_atomic_fetch_add(p, v, __ATOMIC_RELAXED, __HIP_MEMORY_SCOPE_AGENT); }
; #define XB_SPIN(cond, bar) do { unsigned _sp = 0; while (cond) { __builtin_amdgcn_s_sleep(1); \
;     if ((++_sp & 255u) == 0u) { if (xb_ld(&(bar)[XB_TMO])) break; if (_sp > XB_SPIN_CAP) { atomicAdd(&(bar)[XB_TMO], 1u); break; } } } } while (0)
; #define GSYNC() do { XcdBarrier xb_; xb_.bar = (unsigned*)(KARGS()->ws + WS_CTL) + 1024; xb_.x = xb_xcc_id(); xb_.st = (volatile LAS unsigned*)(lds + LDS_XB); xcd_barrier(xb_); } while (0)
; __device__ __forceinline__ void xcd_barrier(const XcdBarrier& b) {
;     asm volatile("s_waitcnt vmcnt(0)" ::: "memory");
;     __syncthreads();
;     if (threadIdx.x == 0) {
;         unsigned* bar = b.bar;
;         __builtin_amdgcn_s_waitcnt(0);
;         unsigned nloc = b.st[0], nx = b.st[1];
;         if (nloc == 0u) { xcd_barrier_complete(bar, b.x, nloc, nx); b.st[0] = nloc; b.st[1] = nx; }
;         const unsigned old = xb_add(&bar[XB_XSUB(b.x)], 1u);
;         const unsigned gen = old / nloc;
;         if (old + 1u == (gen + 1u) * nloc) {
;             __builtin_amdgcn_fence(__ATOMIC_RELEASE, "agent");
;             asm volatile("s_waitcnt vmcnt(0)" ::: "memory");
;             const unsigned og = xb_add(&bar[XB_TOP], 1u);
;             const unsigned tg = og / nx;
;             if (og + 1u == (tg + 1u) * nx) xb_add(&bar[XB_TOPGEN], 1u);
;             else XB_SPIN(xb_ld(&bar[XB_TOPGEN]) == tg, bar);
;             __builtin_amdgcn_fence(__ATOMIC_ACQUIRE, "agent");
;             xb_add(&bar[XB_XGEN(b.x)], 1u);
;             asm volatile("s_waitcnt vmcnt(0)" ::: "memory");
;         } else {
;             XB_SPIN(xb_ld(&bar[XB_XGEN(b.x)]) == gen, bar);
;             __builtin_amdgcn_fence(__ATOMIC_ACQUIRE, "agent");
;             asm volatile("s_waitcnt vmcnt(0)" ::: "memory");
;         }
;     }
;     __syncthreads();
; }
; __global__ void __launch_bounds__(512, 2) fwd_kernel(Args a) {
;     ...
;         GSYNC();
.LBB0_630:
	s_mov_b64 s[8:9], s[0:1]
	s_getreg_b32 s2, hwreg(HW_REG_XCC_ID, 0, 4)
	s_waitcnt vmcnt(0)
	s_waitcnt lgkmcnt(0)
	v_readlane_b32 s6, v255, 0
	v_readlane_b32 s7, v255, 1
	s_barrier
	v_readlane_b32 s4, v255, 40
	s_nop 1
	s_cmp_eq_u32 s4, 0
	s_cbranch_scc1 .Lfs1
	s_and_saveexec_b64 s[4:5], s[6:7]
	s_cbranch_execz .Lfe1
	s_load_dwordx2 s[8:9], s[0:1], 0x128
	v_readlane_b32 s10, v255, 41
	v_readlane_b32 s11, v255, 8
	s_nop 1
	s_and_b32 s11, s11, 7
	s_lshl_b32 s11, s11, 7
	s_addk_i32 s11, 0x6200
	v_mov_b32_e32 v2, 0
	v_mov_b32_e32 v3, 1
	s_add_i32 s10, s10, 1
	s_lshl_b32 s10, s10, 5
	s_waitcnt lgkmcnt(0)
	s_add_u32 s8, s8, s11
	s_addc_u32 s9, s9, 0
	global_atomic_add v2, v3, s[8:9]

; __device__ __forceinline__ unsigned xb_ld(unsigned* p)              { return __hip_atomic_load(p, __ATOMIC_RELAXED, __HIP_MEMORY_SCOPE_AGENT); }
; __device__ __forceinline__ unsigned xb_add(unsigned* p, unsigned v) { return __hip_atomic_fetch_add(p, v, __ATOMIC_RELAXED, __HIP_MEMORY_SCOPE_AGENT); }
; #define XB_SPIN(cond, bar) do { unsigned _sp = 0; while (cond) { __builtin_amdgcn_s_sleep(1); \
;     if ((++_sp & 255u) == 0u) { if (xb_ld(&(bar)[XB_TMO])) break; if (_sp > XB_SPIN_CAP) { atomicAdd(&(bar)[XB_TMO], 1u); break; } } } } while (0)
; __device__ __forceinline__ void xcd_barrier(const XcdBarrier& b) {
;     asm volatile("s_waitcnt vmcnt(0)" ::: "memory");
;     __syncthreads();
;     if (threadIdx.x == 0) {
;         unsigned* bar = b.bar;
;         __builtin_amdgcn_s_waitcnt(0);
;         unsigned nloc = b.st[0], nx = b.st[1];
;         if (nloc == 0u) { xcd_barrier_complete(bar, b.x, nloc, nx); b.st[0] = nloc; b.st[1] = nx; }
;         const unsigned old = xb_add(&bar[XB_XSUB(b.x)], 1u);
;         const unsigned gen = old / nloc;
;         if (old + 1u == (gen + 1u) * nloc) {
;             __builtin_amdgcn_fence(__ATOMIC_RELEASE, "agent");
;             asm volatile("s_waitcnt vmcnt(0)" ::: "memory");
;             const unsigned og = xb_add(&bar[XB_TOP], 1u);
;             const unsigned tg = og / nx;
;             if (og + 1u == (tg + 1u) * nx) xb_add(&bar[XB_TOPGEN], 1u);
;             else XB_SPIN(xb_ld(&bar[XB_TOPGEN]) == tg, bar);
;             __builtin_amdgcn_fence(__ATOMIC_ACQUIRE, "agent");
;             xb_add(&bar[XB_XGEN(b.x)], 1u);
;             asm volatile("s_waitcnt vmcnt(0)" ::: "memory");
;         } else {
;             XB_SPIN(xb_ld(&bar[XB_XGEN(b.x)]) == gen, bar);
;             __builtin_amdgcn_fence(__ATOMIC_ACQUIRE, "agent");
;             asm volatile("s_waitcnt vmcnt(0)" ::: "memory");
;         }
;     }
;     __syncthreads();
; }
.Lfs1:
	s_and_saveexec_b64 s[4:5], s[6:7]
	s_xor_b64 s[6:7], exec, s[4:5]
	s_cbranch_execz .LBB0_683
	v_readlane_b32 s4, v255, 5
	s_load_dwordx2 s[8:9], s[8:9], 0x128
	s_waitcnt vmcnt(0) expcnt(0) lgkmcnt(0)
	v_mov_b32_e32 v0, s4
	ds_read_b32 v3, v0
	v_readlane_b32 s4, v255, 7
	s_and_b32 s2, s2, 15
	s_waitcnt lgkmcnt(0)
	v_cmp_ne_u32_e32 vcc, 0, v3
	v_mov_b32_e32 v0, s4
	ds_read_b32 v2, v0
	s_cbranch_vccnz .LBB0_646
	s_add_u32 s10, s8, 0x1200
	s_addc_u32 s11, s9, 0
	s_add_u32 s12, s8, 0x1400
	s_addc_u32 s13, s9, 0
	s_add_u32 s14, s8, 0x1500
	s_addc_u32 s15, s9, 0
	s_add_u32 s16, s8, 0x1600
	s_addc_u32 s17, s9, 0
	s_add_u32 s52, s8, 0x1700
	s_addc_u32 s53, s9, 0
	s_add_u32 s54, s8, 0x1800
	s_addc_u32 s55, s9, 0
	s_add_u32 s56, s8, 0x1900
	s_addc_u32 s57, s9, 0
	s_add_u32 s58, s8, 0x1a00
	s_addc_u32 s59, s9, 0
	s_add_u32 s60, s8, 0x1b00
	s_addc_u32 s61, s9, 0
	s_add_u32 s62, s8, 0x1c00
	s_addc_u32 s63, s9, 0
	s_add_u32 s64, s8, 0x1d00
	s_addc_u32 s65, s9, 0
	s_add_u32 s66, s8, 0x1e00
	s_addc_u32 s67, s9, 0
	s_add_u32 s68, s8, 0x1f00
	s_addc_u32 s69, s9, 0
	s_add_u32 s70, s8, 0x2000
	s_addc_u32 s71, s9, 0
	s_add_u32 s72, s8, 0x2100
	s_addc_u32 s73, s9, 0
	s_add_u32 s74, s8, 0x2200
	s_addc_u32 s75, s9, 0
	s_add_u32 s76, s8, 0x2300
	s_addc_u32 s77, s9, 0
	s_mov_b32 s4, 1
	s_branch .LBB0_634

; #define LAS __attribute__((address_space(3)))
;     __device__ bool next(int i, Unit& u) const {
;         const long L = (long)i * G + c; if (L >= nwg) return false;
;         int wgid = (int)L; { const int q = nwg / NXCD, r = nwg % NXCD, xcd = wgid % NXCD, off = wgid / NXCD; wgid = (xcd < r ? xcd * (q + 1) : r * (q + 1) + (xcd - r) * q) + off; }
;         const int nig = WGM * nN, gid = wgid / nig, fm = gid * WGM, gsz = (nM - fm) < WGM ? (nM - fm) : WGM;
;         u.pm = fm + ((wgid % nig) % gsz); u.pn = (wgid % nig) / gsz; u.bz = 0;
;         u.a_off = (unsigned)(u.pm * BM) * (unsigned)lda; u.b_off = (unsigned)(u.pn * BM) * (unsigned)ldb; return true;
; __global__ void __launch_bounds__(512, 2) fwd_kernel(Args a) {
;     ...
;         { PH StdSched S; S.init(T, 2048, G, bid, D, D); EpiWin E{ar, ssb + (size_t)(4 * l + 1) * T * 16, (const LAS float*)(lds + LDS_RS)};
;           gemm_phase<EpiWin, StdSched, true>(lds, hb, (const bf16_t*)(wl + W_IN), D, D, D, S, E); }
.Lfj1:
	s_mov_b64 s[6:7], s[0:1]
	v_mov_b32_e32 v0, v236
	s_mov_b32 s4, s94
	v_readlane_b32 s52, v255, 8
	s_waitcnt lgkmcnt(0)
	s_barrier
	v_readlane_b32 s53, v255, 9
	s_load_dwordx2 s[62:63], s[6:7], 0x128
	s_ashr_i32 s53, s52, 31
	s_cmpk_lt_i32 s52, 0x400
	v_mov_b32_e32 v98, v236
	s_cselect_b64 s[6:7], -1, 0
	s_mov_b64 s[56:57], 0
	v_readfirstlane_b32 s2, v98
	s_and_b64 vcc, exec, s[6:7]
	s_mov_b64 s[54:55], 0
	s_cbranch_vccz .LBB0_689
	s_ashr_i32 s5, s52, 31
	s_lshr_b32 s5, s5, 29
	s_add_i32 s5, s52, s5
	s_and_b32 s8, s5, -8
	s_sub_i32 s10, s52, s8
	s_cmp_gt_i32 s10, -1
	s_mov_b64 s[8:9], -1
	s_cbranch_scc0 .LBB0_686
	s_lshl_b32 s11, s10, 7
	s_mov_b64 s[8:9], 0

; __device__ __forceinline__ unsigned xb_ld(unsigned* p)              { return __hip_atomic_load(p, __ATOMIC_RELAXED, __HIP_MEMORY_SCOPE_AGENT); }
; __device__ __forceinline__ unsigned xb_add(unsigned* p, unsigned v) { return __hip_atomic_fetch_add(p, v, __ATOMIC_RELAXED, __HIP_MEMORY_SCOPE_AGENT); }
; #define XB_SPIN(cond, bar) do { unsigned _sp = 0; while (cond) { __builtin_amdgcn_s_sleep(1); \
;     if ((++_sp & 255u) == 0u) { if (xb_ld(&(bar)[XB_TMO])) break; if (_sp > XB_SPIN_CAP) { atomicAdd(&(bar)[XB_TMO], 1u); break; } } } } while (0)
; #define GSYNC() do { XcdBarrier xb_; xb_.bar = (unsigned*)(KARGS()->ws + WS_CTL) + 1024; xb_.x = xb_xcc_id(); xb_.st = (volatile LAS unsigned*)(lds + LDS_XB); xcd_barrier(xb_); } while (0)
; __device__ __forceinline__ void xcd_barrier(const XcdBarrier& b) {
;     asm volatile("s_waitcnt vmcnt(0)" ::: "memory");
;     __syncthreads();
;     if (threadIdx.x == 0) {
;         unsigned* bar = b.bar;
;         __builtin_amdgcn_s_waitcnt(0);
;         unsigned nloc = b.st[0], nx = b.st[1];
;         if (nloc == 0u) { xcd_barrier_complete(bar, b.x, nloc, nx); b.st[0] = nloc; b.st[1] = nx; }
;         const unsigned old = xb_add(&bar[XB_XSUB(b.x)], 1u);
;         const unsigned gen = old / nloc;
;         if (old + 1u == (gen + 1u) * nloc) {
;             __builtin_amdgcn_fence(__ATOMIC_RELEASE, "agent");
;             asm volatile("s_waitcnt vmcnt(0)" ::: "memory");
;             const unsigned og = xb_add(&bar[XB_TOP], 1u);
;             const unsigned tg = og / nx;
;             if (og + 1u == (tg + 1u) * nx) xb_add(&bar[XB_TOPGEN], 1u);
;             else XB_SPIN(xb_ld(&bar[XB_TOPGEN]) == tg, bar);
;             __builtin_amdgcn_fence(__ATOMIC_ACQUIRE, "agent");
;             xb_add(&bar[XB_XGEN(b.x)], 1u);
;             asm volatile("s_waitcnt vmcnt(0)" ::: "memory");
;         } else {
;             XB_SPIN(xb_ld(&bar[XB_XGEN(b.x)]) == gen, bar);
;             __builtin_amdgcn_fence(__ATOMIC_ACQUIRE, "agent");
;             asm volatile("s_waitcnt vmcnt(0)" ::: "memory");
;         }
;     }
;     __syncthreads();
; }
; __global__ void __launch_bounds__(512, 2) fwd_kernel(Args a) {
;     ...
;         GSYNC();
.LBB0_1525:
	s_mov_b64 s[8:9], s[0:1]
	s_getreg_b32 s2, hwreg(HW_REG_XCC_ID, 0, 4)
	s_waitcnt vmcnt(0)
	v_readlane_b32 s6, v255, 0
	v_readlane_b32 s7, v255, 1
	s_waitcnt lgkmcnt(0)
	s_barrier
	v_readlane_b32 s4, v255, 40
	s_nop 1
	s_cmp_eq_u32 s4, 0
	s_cbranch_scc1 .Lfs2
	s_and_saveexec_b64 s[4:5], s[6:7]
	s_cbranch_execz .Lfe2
	s_load_dwordx2 s[8:9], s[0:1], 0x128
	v_readlane_b32 s10, v255, 41
	v_readlane_b32 s11, v255, 8
	s_nop 1
	s_and_b32 s11, s11, 7
	s_lshl_b32 s11, s11, 7
	s_addk_i32 s11, 0x6200
	v_mov_b32_e32 v2, 0
	v_mov_b32_e32 v3, 1
	s_add_i32 s10, s10, 1
	s_lshl_b32 s10, s10, 5
	s_waitcnt lgkmcnt(0)
	s_add_u32 s8, s8, s11
	s_addc_u32 s9, s9, 0
	global_atomic_add v2, v3, s[8:9]

; __device__ __forceinline__ unsigned xb_ld(unsigned* p)              { return __hip_atomic_load(p, __ATOMIC_RELAXED, __HIP_MEMORY_SCOPE_AGENT); }
; __device__ __forceinline__ unsigned xb_add(unsigned* p, unsigned v) { return __hip_atomic_fetch_add(p, v, __ATOMIC_RELAXED, __HIP_MEMORY_SCOPE_AGENT); }
; #define XB_SPIN(cond, bar) do { unsigned _sp = 0; while (cond) { __builtin_amdgcn_s_sleep(1); \
;     if ((++_sp & 255u) == 0u) { if (xb_ld(&(bar)[XB_TMO])) break; if (_sp > XB_SPIN_CAP) { atomicAdd(&(bar)[XB_TMO], 1u); break; } } } } while (0)
; __device__ __forceinline__ void xcd_barrier(const XcdBarrier& b) {
;     asm volatile("s_waitcnt vmcnt(0)" ::: "memory");
;     __syncthreads();
;     if (threadIdx.x == 0) {
;         unsigned* bar = b.bar;
;         __builtin_amdgcn_s_waitcnt(0);
;         unsigned nloc = b.st[0], nx = b.st[1];
;         if (nloc == 0u) { xcd_barrier_complete(bar, b.x, nloc, nx); b.st[0] = nloc; b.st[1] = nx; }
;         const unsigned old = xb_add(&bar[XB_XSUB(b.x)], 1u);
;         const unsigned gen = old / nloc;
;         if (old + 1u == (gen + 1u) * nloc) {
;             __builtin_amdgcn_fence(__ATOMIC_RELEASE, "agent");
;             asm volatile("s_waitcnt vmcnt(0)" ::: "memory");
;             const unsigned og = xb_add(&bar[XB_TOP], 1u);
;             const unsigned tg = og / nx;
;             if (og + 1u == (tg + 1u) * nx) xb_add(&bar[XB_TOPGEN], 1u);
;             else XB_SPIN(xb_ld(&bar[XB_TOPGEN]) == tg, bar);
;             __builtin_amdgcn_fence(__ATOMIC_ACQUIRE, "agent");
;             xb_add(&bar[XB_XGEN(b.x)], 1u);
;             asm volatile("s_waitcnt vmcnt(0)" ::: "memory");
;         } else {
;             XB_SPIN(xb_ld(&bar[XB_XGEN(b.x)]) == gen, bar);
;             __builtin_amdgcn_fence(__ATOMIC_ACQUIRE, "agent");
;             asm volatile("s_waitcnt vmcnt(0)" ::: "memory");
;         }
;     }
;     __syncthreads();
; }
.Lfs2:
	s_and_saveexec_b64 s[4:5], s[6:7]
	s_xor_b64 s[6:7], exec, s[4:5]
	s_cbranch_execz .LBB0_1578
	v_readlane_b32 s4, v255, 5
	s_load_dwordx2 s[8:9], s[8:9], 0x128
	s_waitcnt vmcnt(0) expcnt(0) lgkmcnt(0)
	v_mov_b32_e32 v0, s4
	ds_read_b32 v3, v0
	v_readlane_b32 s4, v255, 7
	s_and_b32 s2, s2, 15
	s_waitcnt lgkmcnt(0)
	v_cmp_ne_u32_e32 vcc, 0, v3
	v_mov_b32_e32 v0, s4
	ds_read_b32 v2, v0
	s_cbranch_vccnz .LBB0_1541
	s_add_u32 s10, s8, 0x1200
	s_addc_u32 s11, s9, 0
	s_add_u32 s12, s8, 0x1400
	s_addc_u32 s13, s9, 0
	s_add_u32 s14, s8, 0x1500
	s_addc_u32 s15, s9, 0
	s_add_u32 s16, s8, 0x1600
	s_addc_u32 s17, s9, 0
	s_add_u32 s48, s8, 0x1700
	s_addc_u32 s49, s9, 0
	s_add_u32 s52, s8, 0x1800
	s_addc_u32 s53, s9, 0
	s_add_u32 s54, s8, 0x1900
	s_addc_u32 s55, s9, 0
	s_add_u32 s56, s8, 0x1a00
	s_addc_u32 s57, s9, 0
	s_add_u32 s58, s8, 0x1b00
	s_addc_u32 s59, s9, 0
	s_add_u32 s60, s8, 0x1c00
	s_addc_u32 s61, s9, 0
	s_add_u32 s62, s8, 0x1d00
	s_addc_u32 s63, s9, 0
	s_add_u32 s64, s8, 0x1e00
	s_addc_u32 s65, s9, 0
	s_add_u32 s66, s8, 0x1f00
	s_addc_u32 s67, s9, 0
	s_add_u32 s68, s8, 0x2000
	s_addc_u32 s69, s9, 0
	s_add_u32 s70, s8, 0x2100
	s_addc_u32 s71, s9, 0
	s_add_u32 s72, s8, 0x2200
	s_addc_u32 s73, s9, 0
	s_add_u32 s74, s8, 0x2300
	s_addc_u32 s75, s9, 0
	s_mov_b32 s4, 1
	s_branch .LBB0_1529

; #define LAS __attribute__((address_space(3)))
;     __device__ bool next(int i, Unit& u) const {
;         const long L = (long)i * G + c; if (L >= nwg) return false;
;         int wgid = (int)L; { const int q = nwg / NXCD, r = nwg % NXCD, xcd = wgid % NXCD, off = wgid / NXCD; wgid = (xcd < r ? xcd * (q + 1) : r * (q + 1) + (xcd - r) * q) + off; }
;         const int nig = WGM * nN, gid = wgid / nig, fm = gid * WGM, gsz = (nM - fm) < WGM ? (nM - fm) : WGM;
;         u.pm = fm + ((wgid % nig) % gsz); u.pn = (wgid % nig) / gsz; u.bz = 0;
;         u.a_off = (unsigned)(u.pm * BM) * (unsigned)lda; u.b_off = (unsigned)(u.pn * BM) * (unsigned)ldb; return true;
; __global__ void __launch_bounds__(512, 2) fwd_kernel(Args a) {
;     ...
;         { PH StdSched S; S.init(T, D, G, bid, D, D); EpiWq E{(bf16_t*)(ar + AR_QX), ssb + (size_t)(4 * l + 2) * T * 16, 0.0625f * LOG2E, (const LAS float*)(lds + LDS_RS)};
;           gemm_phase<EpiWq, StdSched, true>(lds, hb, (const bf16_t*)(wl + W_Q), D, D, D, S, E); }
.Lfj2:
	s_mov_b64 s[4:5], s[0:1]
	v_mov_b32_e32 v0, v236
	s_mov_b32 s10, s94
	v_readlane_b32 s48, v255, 8
	s_waitcnt lgkmcnt(0)
	s_barrier
	v_readlane_b32 s49, v255, 9
	s_load_dwordx2 s[52:53], s[4:5], 0x128
	s_ashr_i32 s49, s48, 31
	s_cmpk_lt_i32 s48, 0x200
	v_mov_b32_e32 v98, v236
	s_cselect_b64 s[6:7], -1, 0
	s_mov_b64 s[56:57], 0
	v_readfirstlane_b32 s62, v98
	s_and_b64 vcc, exec, s[6:7]
	s_mov_b64 s[54:55], 0
	s_cbranch_vccz .LBB0_1584
	s_ashr_i32 s2, s48, 31
	s_lshr_b32 s2, s2, 29
	s_add_i32 s2, s48, s2
	s_and_b32 s4, s2, -8
	s_sub_i32 s4, s48, s4
	s_cmp_gt_i32 s4, -1
	s_mov_b64 s[8:9], -1
	s_cbranch_scc0 .LBB0_1581
	s_lshl_b32 s5, s4, 6
	s_mov_b64 s[8:9], 0

; __device__ __forceinline__ unsigned xb_ld(unsigned* p)              { return __hip_atomic_load(p, __ATOMIC_RELAXED, __HIP_MEMORY_SCOPE_AGENT); }
; __device__ __forceinline__ unsigned xb_add(unsigned* p, unsigned v) { return __hip_atomic_fetch_add(p, v, __ATOMIC_RELAXED, __HIP_MEMORY_SCOPE_AGENT); }
; #define XB_SPIN(cond, bar) do { unsigned _sp = 0; while (cond) { __builtin_amdgcn_s_sleep(1); \
;     if ((++_sp & 255u) == 0u) { if (xb_ld(&(bar)[XB_TMO])) break; if (_sp > XB_SPIN_CAP) { atomicAdd(&(bar)[XB_TMO], 1u); break; } } } } while (0)
; __device__ __forceinline__ void xcd_barrier(const XcdBarrier& b) {
;     asm volatile("s_waitcnt vmcnt(0)" ::: "memory");
;     __syncthreads();
;     if (threadIdx.x == 0) {
;         unsigned* bar = b.bar;
;         __builtin_amdgcn_s_waitcnt(0);
;         unsigned nloc = b.st[0], nx = b.st[1];
;         if (nloc == 0u) { xcd_barrier_complete(bar, b.x, nloc, nx); b.st[0] = nloc; b.st[1] = nx; }
;         const unsigned old = xb_add(&bar[XB_XSUB(b.x)], 1u);
;         const unsigned gen = old / nloc;
;         if (old + 1u == (gen + 1u) * nloc) {
;             __builtin_amdgcn_fence(__ATOMIC_RELEASE, "agent");
;             asm volatile("s_waitcnt vmcnt(0)" ::: "memory");
;             const unsigned og = xb_add(&bar[XB_TOP], 1u);
;             const unsigned tg = og / nx;
;             if (og + 1u == (tg + 1u) * nx) xb_add(&bar[XB_TOPGEN], 1u);
;             else XB_SPIN(xb_ld(&bar[XB_TOPGEN]) == tg, bar);
;             __builtin_amdgcn_fence(__ATOMIC_ACQUIRE, "agent");
;             xb_add(&bar[XB_XGEN(b.x)], 1u);
;             asm volatile("s_waitcnt vmcnt(0)" ::: "memory");
;         } else {
;             XB_SPIN(xb_ld(&bar[XB_XGEN(b.x)]) == gen, bar);
;             __builtin_amdgcn_fence(__ATOMIC_ACQUIRE, "agent");
;             asm volatile("s_waitcnt vmcnt(0)" ::: "memory");
;         }
;     }
;     __syncthreads();
; }
.Lfs3:
	s_and_saveexec_b64 s[4:5], s[6:7]
	s_xor_b64 s[6:7], exec, s[4:5]
	s_cbranch_execz .LBB0_1873
	v_readlane_b32 s4, v255, 5
	s_load_dwordx2 s[8:9], s[8:9], 0x128
	s_waitcnt vmcnt(0) expcnt(0) lgkmcnt(0)
	v_mov_b32_e32 v0, s4
	ds_read_b32 v3, v0
	v_readlane_b32 s4, v255, 7
	s_and_b32 s2, s2, 15
	s_waitcnt lgkmcnt(0)
	v_cmp_ne_u32_e32 vcc, 0, v3
	v_mov_b32_e32 v0, s4
	ds_read_b32 v0, v0
	s_cbranch_vccnz .LBB0_1836
	s_add_u32 s10, s8, 0x1200
	s_addc_u32 s11, s9, 0
	s_add_u32 s12, s8, 0x1400
	s_addc_u32 s13, s9, 0
	s_add_u32 s14, s8, 0x1500
	s_addc_u32 s15, s9, 0
	s_add_u32 s16, s8, 0x1600
	s_addc_u32 s17, s9, 0
	s_add_u32 s48, s8, 0x1700
	s_addc_u32 s49, s9, 0
	s_add_u32 s50, s8, 0x1800
	s_addc_u32 s51, s9, 0
	s_add_u32 s52, s8, 0x1900
	s_addc_u32 s53, s9, 0
	s_add_u32 s54, s8, 0x1a00
	s_addc_u32 s55, s9, 0
	s_add_u32 s56, s8, 0x1b00
	s_addc_u32 s57, s9, 0
	s_add_u32 s58, s8, 0x1c00
	s_addc_u32 s59, s9, 0
	s_add_u32 s60, s8, 0x1d00
	s_addc_u32 s61, s9, 0
	s_add_u32 s62, s8, 0x1e00
	s_addc_u32 s63, s9, 0
	s_add_u32 s64, s8, 0x1f00
	s_addc_u32 s65, s9, 0
	s_add_u32 s66, s8, 0x2000
	s_addc_u32 s67, s9, 0
	s_add_u32 s68, s8, 0x2100
	s_addc_u32 s69, s9, 0
	s_add_u32 s70, s8, 0x2200
	s_addc_u32 s71, s9, 0
	s_add_u32 s72, s8, 0x2300
	s_addc_u32 s73, s9, 0
	s_mov_b32 s4, 1
	s_branch .LBB0_1824

;     __device__ bool next(int i, Unit& u) const {
;         const long L = (long)i * G + c; if (L >= nwg) return false;
;         int wgid = (int)L; { const int q = nwg / NXCD, r = nwg % NXCD, xcd = wgid % NXCD, off = wgid / NXCD; wgid = (xcd < r ? xcd * (q + 1) : r * (q + 1) + (xcd - r) * q) + off; }
;         const int nig = WGM * nN, gid = wgid / nig, fm = gid * WGM, gsz = (nM - fm) < WGM ? (nM - fm) : WGM;
;         u.pm = fm + ((wgid % nig) % gsz); u.pn = (wgid % nig) / gsz; u.bz = 0;
;         u.a_off = (unsigned)(u.pm * BM) * (unsigned)lda; u.b_off = (unsigned)(u.pn * BM) * (unsigned)ldb; return true;
; __global__ void __launch_bounds__(512, 2) fwd_kernel(Args a) {
;     ...
;         { PH StdSched S; S.init(T, D, G, bid, D, D); EpiResid E{hb, ssb + (size_t)(4 * l + 3) * T * 16, (PROBE == 7 && rep == 0) ? 0.f : 1.f, nullptr, nullptr};
;           gemm_phase<EpiResid, StdSched, true>(lds, (const bf16_t*)(ar + AR_OX), (const bf16_t*)(wl + W_O), D, D, D, S, E); }
.Lfj3:
	v_readlane_b32 s6, v255, 8
	s_mov_b64 s[4:5], s[0:1]
	v_readlane_b32 s7, v255, 9
	s_mov_b32 s2, s6
	s_waitcnt lgkmcnt(0)
	v_mov_b32_e32 v0, v236
	s_mov_b32 s16, s94
	s_barrier
	s_load_dwordx2 s[6:7], s[4:5], 0x128
	s_cmpk_lt_i32 s2, 0x200
	v_mov_b32_e32 v10, v236
	s_cselect_b64 s[12:13], -1, 0
	s_mov_b64 s[10:11], 0
	v_readfirstlane_b32 s14, v10
	s_and_b64 vcc, exec, s[12:13]
	s_mov_b64 s[8:9], 0
	s_cbranch_vccz .LBB0_1879
	s_ashr_i32 s4, s2, 31
	s_lshr_b32 s4, s4, 29
	s_add_i32 s4, s2, s4
	s_and_b32 s5, s4, -8
	s_sub_i32 s5, s2, s5
	s_cmp_gt_i32 s5, -1
	s_mov_b64 s[8:9], -1
	s_cbranch_scc0 .LBB0_1876
	s_lshl_b32 s10, s5, 6
	s_mov_b64 s[8:9], 0

; #define LAS __attribute__((address_space(3)))
;     __device__ bool next(int i, Unit& u) const {
;         const long L = (long)i * G + c; if (L >= nwg) return false;
;         int wgid = (int)L; { const int q = nwg / NXCD, r = nwg % NXCD, xcd = wgid % NXCD, off = wgid / NXCD; wgid = (xcd < r ? xcd * (q + 1) : r * (q + 1) + (xcd - r) * q) + off; }
;         const int nig = WGM * nN, gid = wgid / nig, fm = gid * WGM, gsz = (nM - fm) < WGM ? (nM - fm) : WGM;
;         u.pm = fm + ((wgid % nig) % gsz); u.pn = (wgid % nig) / gsz; u.bz = 0;
;         u.a_off = (unsigned)(u.pm * BM) * (unsigned)lda; u.b_off = (unsigned)(u.pn * BM) * (unsigned)ldb; return true;
; __global__ void __launch_bounds__(512, 2) fwd_kernel(Args a) {
;     ...
;         { PH StdSched S; S.init(T, 2 * FF, G, bid, D, D); EpiFfnUp E{(bf16_t*)(ar + AR_HID), ssb + (size_t)(4 * l + 3) * T * 16, (const LAS float*)(lds + LDS_RS)};
;           gemm_phase<EpiFfnUp, StdSched, true>(lds, hb, (const bf16_t*)(wl + W_GU2), D, D, D, S, E); }
.Lfj4:
	s_mov_b64 s[4:5], s[0:1]
	v_readlane_b32 s48, v255, 8
	s_waitcnt lgkmcnt(0)
	v_mov_b32_e32 v0, v236
	s_mov_b32 s8, s94
	s_barrier
	v_readlane_b32 s49, v255, 9
	s_load_dwordx2 s[50:51], s[4:5], 0x128
	s_ashr_i32 s49, s48, 31
	s_cmpk_lt_i32 s48, 0xb00
	v_mov_b32_e32 v98, v236
	s_cselect_b64 s[6:7], -1, 0
	s_mov_b64 s[52:53], 0
	v_readfirstlane_b32 s25, v98
	s_and_b64 vcc, exec, s[6:7]
	s_mov_b64 s[54:55], 0
	s_cbranch_vccz .LBB0_1970
	s_ashr_i32 s2, s48, 31
	s_lshr_b32 s2, s2, 29
	s_add_i32 s2, s48, s2
	s_ashr_i32 s4, s2, 3
	s_and_b32 s2, s2, -8
	s_sub_i32 s2, s48, s2
	s_cmp_lt_i32 s2, 0
	s_movk_i32 s5, 0x161
	s_cselect_b32 s5, s5, 0x160
	s_mul_i32 s2, s2, s5
	s_add_i32 s2, s2, s4
	s_mul_hi_i32 s4, s2, 0x2e8ba2e9
	s_lshr_b32 s5, s4, 31
	s_ashr_i32 s4, s4, 5
	s_add_i32 s4, s4, s5
	s_lshl_b32 s5, s4, 3
	s_mulk_i32 s4, 0xb0
	s_sub_i32 s2, s2, s4
	s_bfe_u32 s4, s2, 0x3001c
	s_add_i32 s4, s2, s4
	s_sext_i32_i16 s9, s4
	s_and_b32 s4, s4, 0xfff8
	s_sub_i32 s2, s2, s4
	s_sext_i32_i16 s2, s2
	s_add_i32 s4, s5, s2
	s_ashr_i32 s5, s9, 3
	s_lshl_b32 s18, s4, 18
	s_lshl_b32 s54, s5, 18
	s_mov_b32 s55, s19
	s_mov_b64 s[52:53], s[18:19]

; __device__ __forceinline__ unsigned xb_ld(unsigned* p)              { return __hip_atomic_load(p, __ATOMIC_RELAXED, __HIP_MEMORY_SCOPE_AGENT); }
; __device__ __forceinline__ unsigned xb_add(unsigned* p, unsigned v) { return __hip_atomic_fetch_add(p, v, __ATOMIC_RELAXED, __HIP_MEMORY_SCOPE_AGENT); }
; #define XB_SPIN(cond, bar) do { unsigned _sp = 0; while (cond) { __builtin_amdgcn_s_sleep(1); \
;     if ((++_sp & 255u) == 0u) { if (xb_ld(&(bar)[XB_TMO])) break; if (_sp > XB_SPIN_CAP) { atomicAdd(&(bar)[XB_TMO], 1u); break; } } } } while (0)
; #define GSYNC() do { XcdBarrier xb_; xb_.bar = (unsigned*)(KARGS()->ws + WS_CTL) + 1024; xb_.x = xb_xcc_id(); xb_.st = (volatile LAS unsigned*)(lds + LDS_XB); xcd_barrier(xb_); } while (0)
; __device__ __forceinline__ void xcd_barrier(const XcdBarrier& b) {
;     asm volatile("s_waitcnt vmcnt(0)" ::: "memory");
;     __syncthreads();
;     if (threadIdx.x == 0) {
;         unsigned* bar = b.bar;
;         __builtin_amdgcn_s_waitcnt(0);
;         unsigned nloc = b.st[0], nx = b.st[1];
;         if (nloc == 0u) { xcd_barrier_complete(bar, b.x, nloc, nx); b.st[0] = nloc; b.st[1] = nx; }
;         const unsigned old = xb_add(&bar[XB_XSUB(b.x)], 1u);
;         const unsigned gen = old / nloc;
;         if (old + 1u == (gen + 1u) * nloc) {
;             __builtin_amdgcn_fence(__ATOMIC_RELEASE, "agent");
;             asm volatile("s_waitcnt vmcnt(0)" ::: "memory");
;             const unsigned og = xb_add(&bar[XB_TOP], 1u);
;             const unsigned tg = og / nx;
;             if (og + 1u == (tg + 1u) * nx) xb_add(&bar[XB_TOPGEN], 1u);
;             else XB_SPIN(xb_ld(&bar[XB_TOPGEN]) == tg, bar);
;             __builtin_amdgcn_fence(__ATOMIC_ACQUIRE, "agent");
;             xb_add(&bar[XB_XGEN(b.x)], 1u);
;             asm volatile("s_waitcnt vmcnt(0)" ::: "memory");
;         } else {
;             XB_SPIN(xb_ld(&bar[XB_XGEN(b.x)]) == gen, bar);
;             __builtin_amdgcn_fence(__ATOMIC_ACQUIRE, "agent");
;             asm volatile("s_waitcnt vmcnt(0)" ::: "memory");
;         }
;     }
;     __syncthreads();
; }
; __global__ void __launch_bounds__(512, 2) fwd_kernel(Args a) {
;     ...
;         GSYNC();
.LBB0_2010:
	s_mov_b64 s[8:9], s[0:1]
	s_getreg_b32 s2, hwreg(HW_REG_XCC_ID, 0, 4)
	s_waitcnt vmcnt(0)
	v_readlane_b32 s6, v255, 0
	v_readlane_b32 s7, v255, 1
	s_waitcnt vmcnt(0) lgkmcnt(0)
	s_barrier
	v_readlane_b32 s4, v255, 40
	s_nop 1
	s_cmp_eq_u32 s4, 0
	s_cbranch_scc1 .Lfs5
	s_and_saveexec_b64 s[4:5], s[6:7]
	s_cbranch_execz .Lfe5
	s_load_dwordx2 s[8:9], s[0:1], 0x128
	v_readlane_b32 s10, v255, 41
	v_readlane_b32 s11, v255, 8
	s_nop 1
	s_and_b32 s11, s11, 7
	s_lshl_b32 s11, s11, 7
	s_addk_i32 s11, 0x6200
	v_mov_b32_e32 v2, 0
	v_mov_b32_e32 v3, 1
	s_add_i32 s10, s10, 1
	s_lshl_b32 s10, s10, 5
	s_waitcnt lgkmcnt(0)
	s_add_u32 s8, s8, s11
	s_addc_u32 s9, s9, 0
	global_atomic_add v2, v3, s[8:9]

;     __device__ bool next(int i, Unit& u) const {
;         const long L = (long)i * G + c; if (L >= nwg) return false;
;         int wgid = (int)L; { const int q = nwg / NXCD, r = nwg % NXCD, xcd = wgid % NXCD, off = wgid / NXCD; wgid = (xcd < r ? xcd * (q + 1) : r * (q + 1) + (xcd - r) * q) + off; }
;         const int nig = WGM * nN, gid = wgid / nig, fm = gid * WGM, gsz = (nM - fm) < WGM ? (nM - fm) : WGM;
;         u.pm = fm + ((wgid % nig) % gsz); u.pn = (wgid % nig) / gsz; u.bz = 0;
;         u.a_off = (unsigned)(u.pm * BM) * (unsigned)lda; u.b_off = (unsigned)(u.pn * BM) * (unsigned)ldb; return true;
; __global__ void __launch_bounds__(512, 2) fwd_kernel(Args a) {
;     ...
;         { PH StdSched S; S.init(T, D, G, bid, FF, FF); EpiResid E{hb, ssb + (size_t)(4 * l + 4) * T * 16, (PROBE == 7 && rep == 0) ? 0.f : 0.5f, nullptr, nullptr};
;           gemm_phase<EpiResid, StdSched, true>(lds, (const bf16_t*)(ar + AR_HID), (const bf16_t*)(wl + W_D2), FF, FF, FF, S, E); }
.Lfj5:
	v_readlane_b32 s6, v255, 8
	s_mov_b64 s[4:5], s[0:1]
	s_waitcnt lgkmcnt(0)
	v_mov_b32_e32 v0, v236
	s_mov_b32 s16, s94
	v_readlane_b32 s7, v255, 9
	s_mov_b32 s2, s6
	s_barrier
	s_load_dwordx2 s[6:7], s[4:5], 0x128
	s_cmpk_lt_i32 s2, 0x200
	v_mov_b32_e32 v10, v236
	s_cselect_b64 s[12:13], -1, 0
	s_mov_b64 s[10:11], 0
	v_readfirstlane_b32 s14, v10
	s_and_b64 vcc, exec, s[12:13]
	s_mov_b64 s[8:9], 0
	s_cbranch_vccz .LBB0_2069
	s_ashr_i32 s4, s2, 31
	s_lshr_b32 s4, s4, 29
	s_add_i32 s4, s2, s4
	s_and_b32 s5, s4, -8
	s_sub_i32 s5, s2, s5
	s_cmp_gt_i32 s5, -1
	s_mov_b64 s[8:9], -1
	s_cbranch_scc0 .LBB0_2066
	s_lshl_b32 s10, s5, 6
	s_mov_b64 s[8:9], 0
